# win: next tile k-tile 1 prefetched into dead acc regs before the epilogue store ladder; prefetched-tile prologue no longer waits for epilogue stores
# baseline (speedup 1.0000x reference)
; #define ZERO_ACC8(acc, NJ_)                             \
;   _Pragma("unroll") for (int i_ = 0; i_ < 8; ++i_)      \
;   _Pragma("unroll") for (int j_ = 0; j_ < (NJ_); ++j_) { acc[i_][j_] = (f32x4){0.f, 0.f, 0.f, 0.f}; }
; template <int MI, int NJ> ...
;     ...
;   if (!pre) G8LOADP(Ag, Bg);
;   G8STORE(0);
;   {
;     const u16* ga_ = (1 < nk) ? Ag + 64 : Ag + nAoff;
;     const u16* gb_ = (1 < nk) ? Bg + 64 : Bg + nBoff;
;     G8LOADP(ga_, gb_);
;   }
;   __syncthreads();
; __device__ __forceinline__ void phase_win(const Params& p, int part, u16* smem, volatile LAS unsigned* vb_) {
;     ...
;   auto ntile = [&](int nl_) { return (part == 0) ? ((nl_ < 6) ? nl_ : (14 + nl_ - 6)) : ((nl_ < 8) ? (6 + nl_) : (20 + nl_ - 8)); };
;   for (int lt = vb >> 3; lt < 8 * NT; lt += step) {
;     const int nl = lt >> 3, mt = (vb & 7) * 8 + (lt & 7);
;     const int nt = ntile(nl);
;     const int ltn = (lt + step < 8 * NT) ? lt + step : lt;
;     const int nmt = (vb & 7) * 8 + (ltn & 7), nnt = ntile(ltn >> 3);
;     u16* dstA; u16* dstB; int ldA, ldB;
;     {
;       const int ct = nt * 2;
;       if (ct < 12) { dstA = (u16*)(p.ws + OFF_UCONV) + ct * 128; ldA = 1536; }
;       else if (ct < 28) { dstA = (u16*)(p.ws + OFF_UHG) + (ct - 12) * 128; ldA = 2048; }
;       else if (ct < 40) { dstA = (u16*)(p.ws + OFF_UNSA) + (ct - 28) * 128; ldA = 1536; }
;       else { dstA = (u16*)(p.ws + OFF_UMG) + (ct - 40) * 128; ldA = 3072; }
;       dstB = dstA + 128; ldB = ldA;
;     }
;     f32x4 acc[8][4];
;     ZERO_ACC8(acc, 4);
;     gemm8<8, 4>(acc, G8REGS_ARGS, pre, H, 1024, W, 1024, 0, 1024, mt * 256, nt * 256, nmt * 256, nnt * 256, 0, smem, tid);
.LBB0_467:
	s_and_b32 s11, s38, 7
	s_or_b32 s10, s11, s23
	s_lshl_b32 s10, s10, 8
	v_add_u32_e32 v34, s10, v184
	v_ashrrev_i32_e32 v35, 31, v34
	v_lshlrev_b64 v[34:35], 11, v[34:35]
	v_lshl_add_u64 v[180:181], v[176:177], 0, v[34:35]
	v_add_u32_e32 v34, s20, v184
	v_ashrrev_i32_e32 v35, 31, v34
	v_lshlrev_b64 v[34:35], 11, v[34:35]
	s_xor_b64 s[12:13], s[12:13], -1
	s_andn2_b64 vcc, exec, s[12:13]
	v_lshl_add_u64 v[182:183], v[178:179], 0, v[34:35]
	v_readfirstlane_b32 s62, v180
	v_readfirstlane_b32 s63, v181
	v_readfirstlane_b32 s64, v182
	v_readfirstlane_b32 s65, v183
	s_nop 4
	s_cbranch_vccnz .Lwin_pre
	global_load_dwordx4 v[10:13], v234, s[62:63]
	global_load_dwordx4 v[2:5], v235, s[62:63]
	global_load_dwordx4 v[6:9], v236, s[62:63]
	global_load_dwordx4 v[18:21], v237, s[62:63]
	global_load_dwordx4 v[14:17], v234, s[64:65]
	global_load_dwordx4 v[22:25], v235, s[64:65]
	global_load_dwordx4 v[26:29], v236, s[64:65]
	global_load_dwordx4 v[30:33], v237, s[64:65]
	s_waitcnt vmcnt(5)
	ds_write_b128 v185, v[10:13]
	ds_write_b128 v185, v[2:5] offset:8192
	ds_write_b128 v185, v[6:9] offset:16384
	s_waitcnt vmcnt(3)
	ds_write_b128 v185, v[18:21] offset:24576
	ds_write_b128 v186, v[14:17]
	s_waitcnt vmcnt(2)
	ds_write_b128 v186, v[22:25] offset:8192
	s_waitcnt vmcnt(1)
	ds_write_b128 v186, v[26:29] offset:16384
	s_waitcnt vmcnt(0)
	ds_write_b128 v186, v[30:33] offset:24576
	global_load_dwordx4 v[10:13], v234, s[62:63] offset:128
	global_load_dwordx4 v[2:5], v235, s[62:63] offset:128
	global_load_dwordx4 v[6:9], v236, s[62:63] offset:128
	global_load_dwordx4 v[18:21], v237, s[62:63] offset:128
	global_load_dwordx4 v[14:17], v234, s[64:65] offset:128
	global_load_dwordx4 v[22:25], v235, s[64:65] offset:128
	global_load_dwordx4 v[26:29], v236, s[64:65] offset:128
	global_load_dwordx4 v[30:33], v237, s[64:65] offset:128
	s_branch .Lwin_join
.Lwin_pre:
	s_waitcnt vmcnt(24)
	ds_write_b128 v185, v[10:13]
	ds_write_b128 v185, v[2:5] offset:8192
	ds_write_b128 v185, v[6:9] offset:16384
	ds_write_b128 v185, v[18:21] offset:24576
	ds_write_b128 v186, v[14:17]
	ds_write_b128 v186, v[22:25] offset:8192
	ds_write_b128 v186, v[26:29] offset:16384
	ds_write_b128 v186, v[30:33] offset:24576
	s_waitcnt vmcnt(16) lgkmcnt(0)
	v_mov_b64_e32 v[10:11], v[98:99]
	v_mov_b64_e32 v[12:13], v[100:101]
	v_mov_b64_e32 v[2:3], v[102:103]
	v_mov_b64_e32 v[4:5], v[104:105]
	v_mov_b64_e32 v[6:7], v[106:107]
	v_mov_b64_e32 v[8:9], v[108:109]
	v_mov_b64_e32 v[18:19], v[110:111]
	v_mov_b64_e32 v[20:21], v[112:113]
	v_mov_b64_e32 v[14:15], v[114:115]
	v_mov_b64_e32 v[16:17], v[116:117]
	v_mov_b64_e32 v[22:23], v[118:119]
	v_mov_b64_e32 v[24:25], v[120:121]
	v_mov_b64_e32 v[26:27], v[122:123]
	v_mov_b64_e32 v[28:29], v[124:125]
	v_mov_b64_e32 v[30:31], v[126:127]
	v_mov_b64_e32 v[32:33], v[128:129]
.Lwin_join:
	s_and_b32 s12, s39, 7
	s_sub_i32 s11, s12, s11
	s_lshl_b32 s12, s11, 8
	s_sub_i32 s11, s46, s37
	s_lshl_b32 s20, s11, 8
	s_ashr_i32 s13, s12, 31
	s_ashr_i32 s21, s20, 31
	v_mov_b32_e32 v34, 0
	s_lshl_b64 s[12:13], s[12:13], 10
	s_lshl_b64 s[46:47], s[20:21], 10
	s_mov_b32 s11, 0
	s_mov_b64 s[20:21], 0x80
	s_mov_b32 s37, 0
	v_mov_b32_e32 v35, v34
	v_mov_b32_e32 v36, v34
	v_mov_b32_e32 v37, v34
	v_mov_b32_e32 v38, v34
	v_mov_b32_e32 v39, v34
	v_mov_b32_e32 v40, v34
	v_mov_b32_e32 v41, v34
	v_mov_b32_e32 v42, v34
	v_mov_b32_e32 v43, v34
	v_mov_b32_e32 v44, v34
	v_mov_b32_e32 v45, v34
	v_mov_b32_e32 v46, v34
	v_mov_b32_e32 v47, v34
	v_mov_b32_e32 v48, v34
	v_mov_b32_e32 v49, v34
	v_mov_b32_e32 v50, v34
	v_mov_b32_e32 v51, v34
	v_mov_b32_e32 v52, v34
	v_mov_b32_e32 v53, v34
	v_mov_b32_e32 v54, v34
	v_mov_b32_e32 v55, v34
	v_mov_b32_e32 v56, v34
	v_mov_b32_e32 v57, v34
	v_mov_b32_e32 v58, v34
	v_mov_b32_e32 v59, v34
	v_mov_b32_e32 v60, v34
	v_mov_b32_e32 v61, v34
	v_mov_b32_e32 v62, v34
	v_mov_b32_e32 v63, v34
	v_mov_b32_e32 v64, v34
	v_mov_b32_e32 v65, v34
	v_mov_b32_e32 v66, v34
	v_mov_b32_e32 v67, v34
	v_mov_b32_e32 v68, v34
	v_mov_b32_e32 v69, v34
	v_mov_b32_e32 v70, v34
	v_mov_b32_e32 v71, v34
	v_mov_b32_e32 v72, v34
	v_mov_b32_e32 v73, v34
	v_mov_b32_e32 v74, v34
	v_mov_b32_e32 v75, v34
	v_mov_b32_e32 v76, v34
	v_mov_b32_e32 v77, v34
	v_mov_b32_e32 v78, v34
	v_mov_b32_e32 v79, v34
	v_mov_b32_e32 v80, v34
	v_mov_b32_e32 v81, v34
	v_mov_b32_e32 v82, v34
	v_mov_b32_e32 v83, v34
	v_mov_b32_e32 v84, v34
	v_mov_b32_e32 v85, v34
	v_mov_b32_e32 v86, v34
	v_mov_b32_e32 v87, v34
	v_mov_b32_e32 v88, v34
	v_mov_b32_e32 v89, v34
	v_mov_b32_e32 v90, v34
	v_mov_b32_e32 v91, v34
	v_mov_b32_e32 v92, v34
	v_mov_b32_e32 v93, v34
	v_mov_b32_e32 v94, v34
	v_mov_b32_e32 v95, v34
	v_mov_b32_e32 v96, v34
	v_mov_b32_e32 v97, v34
	v_mov_b32_e32 v98, v34
	v_mov_b32_e32 v99, v34
	v_mov_b32_e32 v100, v34
	v_mov_b32_e32 v101, v34
	v_mov_b32_e32 v102, v34
	v_mov_b32_e32 v103, v34
	v_mov_b32_e32 v104, v34
	v_mov_b32_e32 v105, v34
	v_mov_b32_e32 v106, v34
	v_mov_b32_e32 v107, v34
	v_mov_b32_e32 v108, v34
	v_mov_b32_e32 v109, v34
	v_mov_b32_e32 v110, v34
	v_mov_b32_e32 v111, v34
	v_mov_b32_e32 v112, v34
	v_mov_b32_e32 v113, v34
	v_mov_b32_e32 v114, v34
	v_mov_b32_e32 v115, v34
	v_mov_b32_e32 v116, v34
	v_mov_b32_e32 v117, v34
	v_mov_b32_e32 v118, v34
	v_mov_b32_e32 v119, v34
	v_mov_b32_e32 v120, v34
	v_mov_b32_e32 v121, v34
	v_mov_b32_e32 v122, v34
	v_mov_b32_e32 v123, v34
	v_mov_b32_e32 v124, v34
	v_mov_b32_e32 v125, v34
	v_mov_b32_e32 v126, v34
	v_mov_b32_e32 v127, v34
	v_mov_b32_e32 v128, v34
	v_mov_b32_e32 v129, v34
	v_mov_b32_e32 v130, v34
	v_mov_b32_e32 v131, v34
	v_mov_b32_e32 v132, v34
	v_mov_b32_e32 v133, v34
	v_mov_b32_e32 v134, v34
	v_mov_b32_e32 v135, v34
	v_mov_b32_e32 v136, v34
	v_mov_b32_e32 v137, v34
	v_mov_b32_e32 v138, v34
	v_mov_b32_e32 v139, v34
	v_mov_b32_e32 v140, v34
	v_mov_b32_e32 v141, v34
	v_mov_b32_e32 v142, v34
	v_mov_b32_e32 v143, v34
	v_mov_b32_e32 v144, v34
	v_mov_b32_e32 v145, v34
	v_mov_b32_e32 v146, v34
	v_mov_b32_e32 v147, v34
	v_mov_b32_e32 v148, v34
	v_mov_b32_e32 v149, v34
	v_mov_b32_e32 v150, v34
	v_mov_b32_e32 v151, v34
	v_mov_b32_e32 v152, v34
	v_mov_b32_e32 v153, v34
	v_mov_b32_e32 v154, v34
	v_mov_b32_e32 v155, v34
	v_mov_b32_e32 v156, v34
	v_mov_b32_e32 v157, v34
	v_mov_b32_e32 v158, v34
	v_mov_b32_e32 v159, v34
	v_mov_b32_e32 v160, v34
	v_mov_b32_e32 v161, v34
	s_waitcnt lgkmcnt(0)
	s_barrier
; template <int MI, int NJ> ...
;     ...
;   for (int kt = 0; kt < nk; ++kt) {
;     const int buf = kt & 1;
;     {
;       G8STORE(buf ^ 1);
;       const u16* ga_ = (kt + 2 < nk) ? Ag + (kt + 2) * 64 : Ag + nAoff;
;       const u16* gb_ = (kt + 2 < nk) ? Bg + (kt + 2) * 64 : Bg + nBoff;
;       G8LOADP(ga_, gb_);
;     }
;     __builtin_amdgcn_sched_barrier(0);
;     __builtin_amdgcn_s_setprio(1);
;     const u16* a = ra_ + buf * AROWS * 64;
;     const u16* b = rb_ + buf * BROWS * 64;
; #pragma unroll
;     for (int ks = 0; ks < 2; ++ks) {
;       const u16* a_ = ks ? a + dsw : a;
;       const u16* b_ = ks ? b + dsw : b;
;       bf16x8 bfr[NJ];
; #pragma unroll
;       for (int j = 0; j < NJ; ++j) bfr[j] = *(const bf16x8*)(b_ + j * 16 * 64);
; #pragma unroll
;       for (int ih = 0; ih < MI / 4; ++ih) {
;         bf16x8 af[4];
; #pragma unroll
;         for (int i = 0; i < 4; ++i) af[i] = *(const bf16x8*)(a_ + (ih * 4 + i) * 16 * 64);
; #pragma unroll
;         for (int i = 0; i < 4; ++i)
; #pragma unroll
;           for (int j = 0; j < NJ; ++j) acc[ih * 4 + i][j] = mfma16(af[i], bfr[j], acc[ih * 4 + i][j]);
;       }
;     }
;     __builtin_amdgcn_s_setprio(0);
;     __builtin_amdgcn_sched_barrier(0);
;     __syncthreads();
	s_and_b32 s38, s11, 0x4000
	s_xor_b32 s39, s38, 0x4000
	s_lshl_b32 s39, s39, 1
	v_add_u32_e32 v228, s39, v185
	v_add_u32_e32 v229, s39, v186
	s_cmp_lt_u32 s37, 14
	s_cselect_b32 s49, s21, s13
	s_cselect_b32 s48, s20, s12
	s_cselect_b32 s51, s21, s47
	s_cselect_b32 s50, s20, s46
	s_lshl_b64 s[48:49], s[48:49], 1
	s_lshl_b64 s[50:51], s[50:51], 1
	s_add_u32 s52, s62, s48
	s_addc_u32 s53, s63, s49
	s_add_u32 s66, s64, s50
	s_addc_u32 s67, s65, s51
	s_lshl_b32 s38, s38, 1
	v_add_u32_e32 v0, s38, v187
	v_add_u32_e32 v191, s38, v188
	ds_read_b128 v[166:169], v191
	ds_read_b128 v[162:165], v0
	ds_read_b128 v[170:173], v191 offset:2048
	ds_read_b128 v[192:195], v191 offset:4096
	ds_read_b128 v[196:199], v191 offset:6144
	ds_read_b128 v[204:207], v0 offset:2048
	ds_read_b128 v[208:211], v0 offset:4096
	ds_read_b128 v[238:241], v0 offset:6144
	v_add_u32_e32 v191, v191, v190
.LBB0_470:
	s_setprio 1
	s_waitcnt lgkmcnt(6)
	v_mfma_f32_16x16x32_bf16 v[158:161], v[166:169], v[162:165], v[158:161]
	s_waitcnt lgkmcnt(5)
	v_mfma_f32_16x16x32_bf16 v[154:157], v[170:173], v[162:165], v[154:157]
	s_waitcnt lgkmcnt(4)
	v_mfma_f32_16x16x32_bf16 v[150:153], v[192:195], v[162:165], v[150:153]
	s_waitcnt lgkmcnt(3)
	v_mfma_f32_16x16x32_bf16 v[146:149], v[196:199], v[162:165], v[146:149]
	ds_read_b128 v[162:165], v0 offset:8192
	s_waitcnt lgkmcnt(3)
	v_mfma_f32_16x16x32_bf16 v[142:145], v[166:169], v[204:207], v[142:145]
	v_mfma_f32_16x16x32_bf16 v[138:141], v[170:173], v[204:207], v[138:141]
	v_mfma_f32_16x16x32_bf16 v[134:137], v[192:195], v[204:207], v[134:137]
	v_mfma_f32_16x16x32_bf16 v[130:133], v[196:199], v[204:207], v[130:133]
	ds_read_b128 v[204:207], v0 offset:10240
	s_waitcnt lgkmcnt(3)
	v_mfma_f32_16x16x32_bf16 v[126:129], v[166:169], v[208:211], v[126:129]
	v_mfma_f32_16x16x32_bf16 v[122:125], v[170:173], v[208:211], v[122:125]
	v_mfma_f32_16x16x32_bf16 v[118:121], v[192:195], v[208:211], v[118:121]
	v_mfma_f32_16x16x32_bf16 v[114:117], v[196:199], v[208:211], v[114:117]
	ds_read_b128 v[208:211], v0 offset:12288
	ds_read_b128 v[212:215], v191
	ds_read_b128 v[216:219], v191 offset:2048
	s_waitcnt lgkmcnt(5)
	v_mfma_f32_16x16x32_bf16 v[110:113], v[166:169], v[238:241], v[110:113]
	v_mfma_f32_16x16x32_bf16 v[106:109], v[170:173], v[238:241], v[106:109]
	v_mfma_f32_16x16x32_bf16 v[102:105], v[192:195], v[238:241], v[102:105]
	v_mfma_f32_16x16x32_bf16 v[98:101], v[196:199], v[238:241], v[98:101]
	ds_read_b128 v[238:241], v0 offset:14336
	ds_read_b128 v[220:223], v191 offset:4096
	ds_read_b128 v[224:227], v191 offset:6144
	s_waitcnt lgkmcnt(7)
	v_mfma_f32_16x16x32_bf16 v[94:97], v[166:169], v[162:165], v[94:97]
	v_mfma_f32_16x16x32_bf16 v[90:93], v[170:173], v[162:165], v[90:93]
	v_mfma_f32_16x16x32_bf16 v[86:89], v[192:195], v[162:165], v[86:89]
	v_mfma_f32_16x16x32_bf16 v[82:85], v[196:199], v[162:165], v[82:85]
	v_add_u32_e32 v0, v0, v190
	ds_read_b128 v[162:165], v0
	s_waitcnt vmcnt(7)
	ds_write_b128 v228, v[10:13]
	global_load_dwordx4 v[10:13], v234, s[52:53]
	s_waitcnt lgkmcnt(8)
	v_mfma_f32_16x16x32_bf16 v[78:81], v[166:169], v[204:207], v[78:81]
	v_mfma_f32_16x16x32_bf16 v[74:77], v[170:173], v[204:207], v[74:77]
	v_mfma_f32_16x16x32_bf16 v[70:73], v[192:195], v[204:207], v[70:73]
	v_mfma_f32_16x16x32_bf16 v[66:69], v[196:199], v[204:207], v[66:69]
	ds_read_b128 v[204:207], v0 offset:2048
	s_waitcnt vmcnt(7)
	ds_write_b128 v228, v[2:5] offset:8192
	global_load_dwordx4 v[2:5], v235, s[52:53]
	s_waitcnt lgkmcnt(9)
	v_mfma_f32_16x16x32_bf16 v[62:65], v[166:169], v[208:211], v[62:65]
	v_mfma_f32_16x16x32_bf16 v[58:61], v[170:173], v[208:211], v[58:61]
	v_mfma_f32_16x16x32_bf16 v[54:57], v[192:195], v[208:211], v[54:57]
	v_mfma_f32_16x16x32_bf16 v[50:53], v[196:199], v[208:211], v[50:53]
	ds_read_b128 v[208:211], v0 offset:4096
	s_waitcnt vmcnt(7)
	ds_write_b128 v228, v[6:9] offset:16384
	global_load_dwordx4 v[6:9], v236, s[52:53]
	s_waitcnt lgkmcnt(8)
	v_mfma_f32_16x16x32_bf16 v[46:49], v[166:169], v[238:241], v[46:49]
	v_mfma_f32_16x16x32_bf16 v[42:45], v[170:173], v[238:241], v[42:45]
	v_mfma_f32_16x16x32_bf16 v[38:41], v[192:195], v[238:241], v[38:41]
	v_mfma_f32_16x16x32_bf16 v[34:37], v[196:199], v[238:241], v[34:37]
	ds_read_b128 v[238:241], v0 offset:6144
	s_waitcnt vmcnt(7)
	ds_write_b128 v228, v[18:21] offset:24576
	global_load_dwordx4 v[18:21], v237, s[52:53]
	s_waitcnt lgkmcnt(7)
	v_mfma_f32_16x16x32_bf16 v[158:161], v[212:215], v[162:165], v[158:161]
	v_mfma_f32_16x16x32_bf16 v[154:157], v[216:219], v[162:165], v[154:157]
	v_mfma_f32_16x16x32_bf16 v[150:153], v[220:223], v[162:165], v[150:153]
	v_mfma_f32_16x16x32_bf16 v[146:149], v[224:227], v[162:165], v[146:149]
	ds_read_b128 v[162:165], v0 offset:8192
	s_waitcnt vmcnt(7)
	ds_write_b128 v229, v[14:17]
	global_load_dwordx4 v[14:17], v234, s[66:67]
	s_waitcnt lgkmcnt(7)
	v_mfma_f32_16x16x32_bf16 v[142:145], v[212:215], v[204:207], v[142:145]
	v_mfma_f32_16x16x32_bf16 v[138:141], v[216:219], v[204:207], v[138:141]
	v_mfma_f32_16x16x32_bf16 v[134:137], v[220:223], v[204:207], v[134:137]
	v_mfma_f32_16x16x32_bf16 v[130:133], v[224:227], v[204:207], v[130:133]
	ds_read_b128 v[204:207], v0 offset:10240
	s_waitcnt vmcnt(7)
	ds_write_b128 v229, v[22:25] offset:8192
	global_load_dwordx4 v[22:25], v235, s[66:67]
	s_waitcnt lgkmcnt(7)
	v_mfma_f32_16x16x32_bf16 v[126:129], v[212:215], v[208:211], v[126:129]
	v_mfma_f32_16x16x32_bf16 v[122:125], v[216:219], v[208:211], v[122:125]
	v_mfma_f32_16x16x32_bf16 v[118:121], v[220:223], v[208:211], v[118:121]
	v_mfma_f32_16x16x32_bf16 v[114:117], v[224:227], v[208:211], v[114:117]
	ds_read_b128 v[208:211], v0 offset:12288
	s_waitcnt vmcnt(7)
	ds_write_b128 v229, v[26:29] offset:16384
	global_load_dwordx4 v[26:29], v236, s[66:67]
	s_waitcnt lgkmcnt(7)
	v_mfma_f32_16x16x32_bf16 v[110:113], v[212:215], v[238:241], v[110:113]
	v_mfma_f32_16x16x32_bf16 v[106:109], v[216:219], v[238:241], v[106:109]
	v_mfma_f32_16x16x32_bf16 v[102:105], v[220:223], v[238:241], v[102:105]
	v_mfma_f32_16x16x32_bf16 v[98:101], v[224:227], v[238:241], v[98:101]
	ds_read_b128 v[238:241], v0 offset:14336
	s_waitcnt vmcnt(7)
	ds_write_b128 v229, v[30:33] offset:24576
	global_load_dwordx4 v[30:33], v237, s[66:67]
	s_waitcnt lgkmcnt(7)
	v_mfma_f32_16x16x32_bf16 v[94:97], v[212:215], v[162:165], v[94:97]
	v_mfma_f32_16x16x32_bf16 v[90:93], v[216:219], v[162:165], v[90:93]
	v_mfma_f32_16x16x32_bf16 v[86:89], v[220:223], v[162:165], v[86:89]
	v_mfma_f32_16x16x32_bf16 v[82:85], v[224:227], v[162:165], v[82:85]
	s_waitcnt lgkmcnt(0)
	s_setprio 0
	s_barrier
; template <int MI, int NJ> ...
;     ...
;   for (int kt = 0; kt < nk; ++kt) {
;     const int buf = kt & 1;
;     {
;       G8STORE(buf ^ 1);
;       const u16* ga_ = (kt + 2 < nk) ? Ag + (kt + 2) * 64 : Ag + nAoff;
;       const u16* gb_ = (kt + 2 < nk) ? Bg + (kt + 2) * 64 : Bg + nBoff;
;       G8LOADP(ga_, gb_);
;     }
;     __builtin_amdgcn_sched_barrier(0);
;     __builtin_amdgcn_s_setprio(1);
;     const u16* a = ra_ + buf * AROWS * 64;
;     const u16* b = rb_ + buf * BROWS * 64;
; #pragma unroll
;     for (int ks = 0; ks < 2; ++ks) {
;       const u16* a_ = ks ? a + dsw : a;
;       const u16* b_ = ks ? b + dsw : b;
;       bf16x8 bfr[NJ];
; #pragma unroll
;       for (int j = 0; j < NJ; ++j) bfr[j] = *(const bf16x8*)(b_ + j * 16 * 64);
; #pragma unroll
;       for (int ih = 0; ih < MI / 4; ++ih) {
;         bf16x8 af[4];
; #pragma unroll
;         for (int i = 0; i < 4; ++i) af[i] = *(const bf16x8*)(a_ + (ih * 4 + i) * 16 * 64);
; #pragma unroll
;         for (int i = 0; i < 4; ++i)
; #pragma unroll
;           for (int j = 0; j < NJ; ++j) acc[ih * 4 + i][j] = mfma16(af[i], bfr[j], acc[ih * 4 + i][j]);
;       }
;     }
;     __builtin_amdgcn_s_setprio(0);
;     __builtin_amdgcn_sched_barrier(0);
;     __syncthreads();
; __device__ __forceinline__ void phase_win(const Params& p, int part, u16* smem, volatile LAS unsigned* vb_) {
;     ...
; #pragma unroll
;     for (int i = 0; i < 8; ++i)
; #pragma unroll
;       for (int j = 0; j < 4; ++j)
; #pragma unroll
;         for (int r = 0; r < 4; ++r)
;           smem[(wm * 128 + i * 16 + (lane >> 4) * 4 + r) * 264 + wn * 64 + j * 16 + (lane & 15)] = f2bf(acc[i][j][r]);
;     __syncthreads();
	s_add_i32 s37, s37, 1
	s_add_u32 s20, s20, 64
	s_addc_u32 s21, s21, 0
	s_addk_i32 s11, 0x4000
	s_and_b32 s38, s11, 0x4000
	s_xor_b32 s39, s38, 0x4000
	s_lshl_b32 s39, s39, 1
	v_add_u32_e32 v228, s39, v185
	v_add_u32_e32 v229, s39, v186
	s_cmp_lt_u32 s37, 14
	s_cselect_b32 s49, s21, s13
	s_cselect_b32 s48, s20, s12
	s_cselect_b32 s51, s21, s47
	s_cselect_b32 s50, s20, s46
	s_lshl_b64 s[48:49], s[48:49], 1
	s_lshl_b64 s[50:51], s[50:51], 1
	s_add_u32 s52, s62, s48
	s_addc_u32 s53, s63, s49
	s_add_u32 s66, s64, s50
	s_addc_u32 s67, s65, s51
	s_lshl_b32 s38, s38, 1
	v_add_u32_e32 v0, s38, v187
	v_add_u32_e32 v191, s38, v188
	s_setprio 1
	ds_read_b128 v[166:169], v191
	ds_read_b128 v[162:165], v0
	ds_read_b128 v[170:173], v191 offset:2048
	ds_read_b128 v[192:195], v191 offset:4096
	ds_read_b128 v[196:199], v191 offset:6144
	v_mfma_f32_16x16x32_bf16 v[78:81], v[212:215], v[204:207], v[78:81]
	v_mfma_f32_16x16x32_bf16 v[74:77], v[216:219], v[204:207], v[74:77]
	v_mfma_f32_16x16x32_bf16 v[70:73], v[220:223], v[204:207], v[70:73]
	v_mfma_f32_16x16x32_bf16 v[66:69], v[224:227], v[204:207], v[66:69]
	ds_read_b128 v[204:207], v0 offset:2048
	v_mfma_f32_16x16x32_bf16 v[62:65], v[212:215], v[208:211], v[62:65]
	v_mfma_f32_16x16x32_bf16 v[58:61], v[216:219], v[208:211], v[58:61]
	v_mfma_f32_16x16x32_bf16 v[54:57], v[220:223], v[208:211], v[54:57]
	v_mfma_f32_16x16x32_bf16 v[50:53], v[224:227], v[208:211], v[50:53]
	ds_read_b128 v[208:211], v0 offset:4096
	v_mfma_f32_16x16x32_bf16 v[46:49], v[212:215], v[238:241], v[46:49]
	v_mfma_f32_16x16x32_bf16 v[42:45], v[216:219], v[238:241], v[42:45]
	v_mfma_f32_16x16x32_bf16 v[38:41], v[220:223], v[238:241], v[38:41]
	v_mfma_f32_16x16x32_bf16 v[34:37], v[224:227], v[238:241], v[34:37]
	ds_read_b128 v[238:241], v0 offset:6144
	v_add_u32_e32 v191, v191, v190
	s_setprio 0
	s_cmpk_lg_i32 s20, 0x480
	s_cbranch_scc1 .LBB0_470
	v_and_b32_e32 v228, 15, v175
	v_bfe_u32 v229, v175, 8, 1
	v_lshl_or_b32 v228, v229, 7, v228
	v_mul_u32_u24_e32 v228, 0x210, v228
	v_bfe_u32 v229, v175, 6, 2
	v_lshl_add_u32 v228, v229, 7, v228
	v_bfe_u32 v229, v175, 4, 2
	v_lshl_add_u32 v228, v229, 3, v228
	v_cvt_pk_bf16_f32 v158, v158, v159
	v_cvt_pk_bf16_f32 v159, v160, v161
	v_cvt_pk_bf16_f32 v154, v154, v155
	v_cvt_pk_bf16_f32 v155, v156, v157
	v_cvt_pk_bf16_f32 v150, v150, v151
	v_cvt_pk_bf16_f32 v151, v152, v153
	v_cvt_pk_bf16_f32 v146, v146, v147
	v_cvt_pk_bf16_f32 v147, v148, v149
	ds_write_b64 v228, v[158:159]
	ds_write_b64 v228, v[154:155] offset:32
	ds_write_b64 v228, v[150:151] offset:64
	ds_write_b64 v228, v[146:147] offset:96
	v_cvt_pk_bf16_f32 v142, v142, v143
	v_cvt_pk_bf16_f32 v143, v144, v145
	v_cvt_pk_bf16_f32 v138, v138, v139
	v_cvt_pk_bf16_f32 v139, v140, v141
	v_cvt_pk_bf16_f32 v134, v134, v135
	v_cvt_pk_bf16_f32 v135, v136, v137
	v_cvt_pk_bf16_f32 v130, v130, v131
	v_cvt_pk_bf16_f32 v131, v132, v133
	ds_write_b64 v228, v[142:143] offset:8448
	ds_write_b64 v228, v[138:139] offset:8480
	ds_write_b64 v228, v[134:135] offset:8512
	ds_write_b64 v228, v[130:131] offset:8544
	v_cvt_pk_bf16_f32 v126, v126, v127
	v_cvt_pk_bf16_f32 v127, v128, v129
	v_cvt_pk_bf16_f32 v122, v122, v123
	v_cvt_pk_bf16_f32 v123, v124, v125
	v_cvt_pk_bf16_f32 v118, v118, v119
	v_cvt_pk_bf16_f32 v119, v120, v121
	v_cvt_pk_bf16_f32 v114, v114, v115
	v_cvt_pk_bf16_f32 v115, v116, v117
	ds_write_b64 v228, v[126:127] offset:16896
	ds_write_b64 v228, v[122:123] offset:16928
	ds_write_b64 v228, v[118:119] offset:16960
	ds_write_b64 v228, v[114:115] offset:16992
	v_cvt_pk_bf16_f32 v110, v110, v111
	v_cvt_pk_bf16_f32 v111, v112, v113
	v_cvt_pk_bf16_f32 v106, v106, v107
	v_cvt_pk_bf16_f32 v107, v108, v109
	v_cvt_pk_bf16_f32 v102, v102, v103
	v_cvt_pk_bf16_f32 v103, v104, v105
	v_cvt_pk_bf16_f32 v98, v98, v99
	v_cvt_pk_bf16_f32 v99, v100, v101
	ds_write_b64 v228, v[110:111] offset:25344
	ds_write_b64 v228, v[106:107] offset:25376
	ds_write_b64 v228, v[102:103] offset:25408
	ds_write_b64 v228, v[98:99] offset:25440
	v_cvt_pk_bf16_f32 v94, v94, v95
	v_cvt_pk_bf16_f32 v95, v96, v97
	v_cvt_pk_bf16_f32 v90, v90, v91
	v_cvt_pk_bf16_f32 v91, v92, v93
	v_cvt_pk_bf16_f32 v86, v86, v87
	v_cvt_pk_bf16_f32 v87, v88, v89
	v_cvt_pk_bf16_f32 v82, v82, v83
	v_cvt_pk_bf16_f32 v83, v84, v85
	ds_write_b64 v228, v[94:95] offset:33792
	ds_write_b64 v228, v[90:91] offset:33824
	ds_write_b64 v228, v[86:87] offset:33856
	ds_write_b64 v228, v[82:83] offset:33888
	v_cvt_pk_bf16_f32 v78, v78, v79
	v_cvt_pk_bf16_f32 v79, v80, v81
	v_cvt_pk_bf16_f32 v74, v74, v75
	v_cvt_pk_bf16_f32 v75, v76, v77
	v_cvt_pk_bf16_f32 v70, v70, v71
	v_cvt_pk_bf16_f32 v71, v72, v73
	v_cvt_pk_bf16_f32 v66, v66, v67
	v_cvt_pk_bf16_f32 v67, v68, v69
	ds_write_b64 v228, v[78:79] offset:42240
	ds_write_b64 v228, v[74:75] offset:42272
	ds_write_b64 v228, v[70:71] offset:42304
	ds_write_b64 v228, v[66:67] offset:42336
	v_cvt_pk_bf16_f32 v62, v62, v63
	v_cvt_pk_bf16_f32 v63, v64, v65
	v_cvt_pk_bf16_f32 v58, v58, v59
	v_cvt_pk_bf16_f32 v59, v60, v61
	v_cvt_pk_bf16_f32 v54, v54, v55
	v_cvt_pk_bf16_f32 v55, v56, v57
	v_cvt_pk_bf16_f32 v50, v50, v51
	v_cvt_pk_bf16_f32 v51, v52, v53
	ds_write_b64 v228, v[62:63] offset:50688
	ds_write_b64 v228, v[58:59] offset:50720
	ds_write_b64 v228, v[54:55] offset:50752
	ds_write_b64 v228, v[50:51] offset:50784
	v_cvt_pk_bf16_f32 v46, v46, v47
	v_cvt_pk_bf16_f32 v47, v48, v49
	v_cvt_pk_bf16_f32 v42, v42, v43
	v_cvt_pk_bf16_f32 v43, v44, v45
	v_cvt_pk_bf16_f32 v38, v38, v39
	v_cvt_pk_bf16_f32 v39, v40, v41
	v_cvt_pk_bf16_f32 v34, v34, v35
	v_cvt_pk_bf16_f32 v35, v36, v37
	ds_write_b64 v228, v[46:47] offset:59136
	ds_write_b64 v228, v[42:43] offset:59168
	ds_write_b64 v228, v[38:39] offset:59200
	ds_write_b64 v228, v[34:35] offset:59232
	v_mov_b32_e32 v43, v175
	s_waitcnt lgkmcnt(0)
	s_barrier
; #define RTID opaque_tid()
; __device__ __forceinline__ void phase_win(const Params& p, int part, u16* smem, volatile LAS unsigned* vb_) {
;     ...
;     const int tid2 = RTID;
; #pragma unroll
;     for (int k = 0; k < 16; ++k) {
;       const int c = tid2 + 512 * k;
;       const int row = c >> 5, ch = c & 31;
;       const uint4 v = *(const uint4*)(smem + row * 264 + ch * 8);
;       u16* d_ = (ch < 16) ? dstA : dstB;
;       const int l_ = (ch < 16) ? ldA : ldB;
;       *(uint4*)(d_ + (size_t)(mt * 256 + row) * l_ + (ch & 15) * 8) = v;
;     }
	global_load_dwordx4 v[98:101], v234, s[52:53] offset:128
	global_load_dwordx4 v[102:105], v235, s[52:53] offset:128
	global_load_dwordx4 v[106:109], v236, s[52:53] offset:128
	global_load_dwordx4 v[110:113], v237, s[52:53] offset:128
	global_load_dwordx4 v[114:117], v234, s[66:67] offset:128
	global_load_dwordx4 v[118:121], v235, s[66:67] offset:128
	global_load_dwordx4 v[122:125], v236, s[66:67] offset:128
	global_load_dwordx4 v[126:129], v237, s[66:67] offset:128
	s_mov_b32 s38, s36
	v_and_b32_e32 v0, 31, v43
	v_lshlrev_b32_e32 v42, 4, v0
	v_cmp_gt_u32_e32 vcc, 16, v0
	v_mov_b32_e32 v0, 0x100
	s_nop 0
	v_cndmask_b32_e64 v0, v0, 0, vcc
	v_lshl_add_u64 v[34:35], s[44:45], 0, v[0:1]
	v_lshlrev_b32_e32 v0, 4, v43
	v_and_b32_e32 v0, 0xf0, v0
	v_lshl_add_u64 v[44:45], v[34:35], 0, v[0:1]
	v_ashrrev_i32_e32 v0, 5, v43
	v_mad_u64_u32 v[34:35], s[12:13], v0, s2, v[42:43]
	v_add_u32_e32 v0, s10, v0
	ds_read_b128 v[34:37], v34
	v_ashrrev_i32_e32 v38, 31, v0
	v_mul_lo_u32 v40, s0, v38
	v_mul_lo_u32 v41, s1, v0
	v_mad_u64_u32 v[38:39], s[12:13], s0, v0, 0
	v_add_u32_e32 v0, 0x200, v43
	v_add3_u32 v39, v39, v40, v41
	v_ashrrev_i32_e32 v0, 5, v0
	v_lshl_add_u64 v[46:47], v[38:39], 1, v[44:45]
	v_mad_u64_u32 v[38:39], s[12:13], v0, s2, v[42:43]
	ds_read_b128 v[38:41], v38
	v_add_u32_e32 v0, s10, v0
	s_waitcnt lgkmcnt(1)
	global_store_dwordx4 v[46:47], v[34:37], off
	s_and_b64 vcc, exec, s[42:43]
	s_nop 0
	v_ashrrev_i32_e32 v34, 31, v0
	v_mul_lo_u32 v36, s0, v34
	v_mul_lo_u32 v37, s1, v0
	v_mad_u64_u32 v[34:35], s[12:13], s0, v0, 0
	v_add3_u32 v35, v35, v36, v37
	v_add_u32_e32 v0, 0x400, v43
	v_lshl_add_u64 v[34:35], v[34:35], 1, v[44:45]
	v_ashrrev_i32_e32 v0, 5, v0
	s_waitcnt lgkmcnt(0)
	global_store_dwordx4 v[34:35], v[38:41], off
	v_mad_u64_u32 v[34:35], s[12:13], v0, s2, v[42:43]
	v_add_u32_e32 v0, s10, v0
	ds_read_b128 v[34:37], v34
	v_ashrrev_i32_e32 v38, 31, v0
	v_mul_lo_u32 v40, s0, v38
	v_mul_lo_u32 v41, s1, v0
	v_mad_u64_u32 v[38:39], s[12:13], s0, v0, 0
	v_add_u32_e32 v0, 0x600, v43
	v_add3_u32 v39, v39, v40, v41
	v_ashrrev_i32_e32 v0, 5, v0
	v_lshl_add_u64 v[46:47], v[38:39], 1, v[44:45]
	v_mad_u64_u32 v[38:39], s[12:13], v0, s2, v[42:43]
	ds_read_b128 v[38:41], v38
	v_add_u32_e32 v0, s10, v0
	s_waitcnt lgkmcnt(1)
	global_store_dwordx4 v[46:47], v[34:37], off
	s_nop 1
	v_ashrrev_i32_e32 v34, 31, v0
	v_mul_lo_u32 v36, s0, v34
	v_mul_lo_u32 v37, s1, v0
	v_mad_u64_u32 v[34:35], s[12:13], s0, v0, 0
	v_add3_u32 v35, v35, v36, v37
	v_add_u32_e32 v0, 0x800, v43
	v_lshl_add_u64 v[34:35], v[34:35], 1, v[44:45]
	v_ashrrev_i32_e32 v0, 5, v0
	s_waitcnt lgkmcnt(0)
	global_store_dwordx4 v[34:35], v[38:41], off
	v_mad_u64_u32 v[34:35], s[12:13], v0, s2, v[42:43]
	v_add_u32_e32 v0, s10, v0
	ds_read_b128 v[34:37], v34
	v_ashrrev_i32_e32 v38, 31, v0
	v_mul_lo_u32 v40, s0, v38
	v_mul_lo_u32 v41, s1, v0
	v_mad_u64_u32 v[38:39], s[12:13], s0, v0, 0
	v_add_u32_e32 v0, 0xa00, v43
	v_add3_u32 v39, v39, v40, v41
	v_ashrrev_i32_e32 v0, 5, v0
	v_lshl_add_u64 v[46:47], v[38:39], 1, v[44:45]
	v_mad_u64_u32 v[38:39], s[12:13], v0, s2, v[42:43]
	ds_read_b128 v[38:41], v38
	v_add_u32_e32 v0, s10, v0
	s_waitcnt lgkmcnt(1)
	global_store_dwordx4 v[46:47], v[34:37], off
	s_nop 1
	v_ashrrev_i32_e32 v34, 31, v0
	v_mul_lo_u32 v36, s0, v34
	v_mul_lo_u32 v37, s1, v0
	v_mad_u64_u32 v[34:35], s[12:13], s0, v0, 0
	v_add3_u32 v35, v35, v36, v37
	v_add_u32_e32 v0, 0xc00, v43
	v_lshl_add_u64 v[34:35], v[34:35], 1, v[44:45]
	v_ashrrev_i32_e32 v0, 5, v0
	s_waitcnt lgkmcnt(0)
	global_store_dwordx4 v[34:35], v[38:41], off
	v_mad_u64_u32 v[34:35], s[12:13], v0, s2, v[42:43]
	v_add_u32_e32 v0, s10, v0
	ds_read_b128 v[34:37], v34
	v_ashrrev_i32_e32 v38, 31, v0
	v_mul_lo_u32 v40, s0, v38
	v_mul_lo_u32 v41, s1, v0
	v_mad_u64_u32 v[38:39], s[12:13], s0, v0, 0
	v_add_u32_e32 v0, 0xe00, v43
	v_add3_u32 v39, v39, v40, v41
	v_ashrrev_i32_e32 v0, 5, v0
	v_lshl_add_u64 v[46:47], v[38:39], 1, v[44:45]
	v_mad_u64_u32 v[38:39], s[12:13], v0, s2, v[42:43]
	ds_read_b128 v[38:41], v38
	v_add_u32_e32 v0, s10, v0
	s_waitcnt lgkmcnt(1)
; __device__ __forceinline__ void phase_win(const Params& p, int part, u16* smem, volatile LAS unsigned* vb_) {
;     ...
; #pragma unroll
;     for (int k = 0; k < 16; ++k) {
;       const int c = tid2 + 512 * k;
;       const int row = c >> 5, ch = c & 31;
;       const uint4 v = *(const uint4*)(smem + row * 264 + ch * 8);
;       u16* d_ = (ch < 16) ? dstA : dstB;
;       const int l_ = (ch < 16) ? ldA : ldB;
;       *(uint4*)(d_ + (size_t)(mt * 256 + row) * l_ + (ch & 15) * 8) = v;
;     }
;     __syncthreads();
;   }
	global_store_dwordx4 v[46:47], v[34:37], off
	s_nop 1
	v_ashrrev_i32_e32 v34, 31, v0
	v_mul_lo_u32 v36, s0, v34
	v_mul_lo_u32 v37, s1, v0
	v_mad_u64_u32 v[34:35], s[12:13], s0, v0, 0
	v_add3_u32 v35, v35, v36, v37
	v_add_u32_e32 v0, 0x1000, v43
	v_lshl_add_u64 v[34:35], v[34:35], 1, v[44:45]
	v_ashrrev_i32_e32 v0, 5, v0
	s_waitcnt lgkmcnt(0)
	global_store_dwordx4 v[34:35], v[38:41], off
	v_mad_u64_u32 v[34:35], s[12:13], v0, s2, v[42:43]
	v_add_u32_e32 v0, s10, v0
	ds_read_b128 v[34:37], v34
	v_ashrrev_i32_e32 v38, 31, v0
	v_mul_lo_u32 v40, s0, v38
	v_mul_lo_u32 v41, s1, v0
	v_mad_u64_u32 v[38:39], s[12:13], s0, v0, 0
	v_add_u32_e32 v0, 0x1200, v43
	v_add3_u32 v39, v39, v40, v41
	v_ashrrev_i32_e32 v0, 5, v0
	v_lshl_add_u64 v[46:47], v[38:39], 1, v[44:45]
	v_mad_u64_u32 v[38:39], s[12:13], v0, s2, v[42:43]
	ds_read_b128 v[38:41], v38
	v_add_u32_e32 v0, s10, v0
	s_waitcnt lgkmcnt(1)
	global_store_dwordx4 v[46:47], v[34:37], off
	s_nop 1
	v_ashrrev_i32_e32 v34, 31, v0
	v_mul_lo_u32 v36, s0, v34
	v_mul_lo_u32 v37, s1, v0
	v_mad_u64_u32 v[34:35], s[12:13], s0, v0, 0
	v_add3_u32 v35, v35, v36, v37
	v_add_u32_e32 v0, 0x1400, v43
	v_lshl_add_u64 v[34:35], v[34:35], 1, v[44:45]
	v_ashrrev_i32_e32 v0, 5, v0
	s_waitcnt lgkmcnt(0)
	global_store_dwordx4 v[34:35], v[38:41], off
	v_mad_u64_u32 v[34:35], s[12:13], v0, s2, v[42:43]
	v_add_u32_e32 v0, s10, v0
	ds_read_b128 v[34:37], v34
	v_ashrrev_i32_e32 v38, 31, v0
	v_mul_lo_u32 v40, s0, v38
	v_mul_lo_u32 v41, s1, v0
	v_mad_u64_u32 v[38:39], s[12:13], s0, v0, 0
	v_add_u32_e32 v0, 0x1600, v43
	v_add3_u32 v39, v39, v40, v41
	v_ashrrev_i32_e32 v0, 5, v0
	v_lshl_add_u64 v[46:47], v[38:39], 1, v[44:45]
	v_mad_u64_u32 v[38:39], s[12:13], v0, s2, v[42:43]
	ds_read_b128 v[38:41], v38
	v_add_u32_e32 v0, s10, v0
	s_waitcnt lgkmcnt(1)
	global_store_dwordx4 v[46:47], v[34:37], off
	s_nop 1
	v_ashrrev_i32_e32 v34, 31, v0
	v_mul_lo_u32 v36, s0, v34
	v_mul_lo_u32 v37, s1, v0
	v_mad_u64_u32 v[34:35], s[12:13], s0, v0, 0
	v_add3_u32 v35, v35, v36, v37
	v_add_u32_e32 v0, 0x1800, v43
	v_lshl_add_u64 v[34:35], v[34:35], 1, v[44:45]
	v_ashrrev_i32_e32 v0, 5, v0
	s_waitcnt lgkmcnt(0)
	global_store_dwordx4 v[34:35], v[38:41], off
	v_mad_u64_u32 v[34:35], s[12:13], v0, s2, v[42:43]
	v_add_u32_e32 v0, s10, v0
	ds_read_b128 v[34:37], v34
	v_ashrrev_i32_e32 v38, 31, v0
	v_mul_lo_u32 v40, s0, v38
	v_mul_lo_u32 v41, s1, v0
	v_mad_u64_u32 v[38:39], s[12:13], s0, v0, 0
	v_add_u32_e32 v0, 0x1a00, v43
	v_add3_u32 v39, v39, v40, v41
	v_ashrrev_i32_e32 v0, 5, v0
	v_lshl_add_u64 v[46:47], v[38:39], 1, v[44:45]
	v_mad_u64_u32 v[38:39], s[12:13], v0, s2, v[42:43]
	ds_read_b128 v[38:41], v38
	v_add_u32_e32 v0, s10, v0
	s_waitcnt lgkmcnt(1)
	global_store_dwordx4 v[46:47], v[34:37], off
	s_nop 1
	v_ashrrev_i32_e32 v34, 31, v0
	v_mul_lo_u32 v36, s0, v34
	v_mul_lo_u32 v37, s1, v0
	v_mad_u64_u32 v[34:35], s[12:13], s0, v0, 0
	v_add3_u32 v35, v35, v36, v37
	v_add_u32_e32 v0, 0x1c00, v43
	v_lshl_add_u64 v[34:35], v[34:35], 1, v[44:45]
	v_ashrrev_i32_e32 v0, 5, v0
	s_waitcnt lgkmcnt(0)
	global_store_dwordx4 v[34:35], v[38:41], off
	v_mad_u64_u32 v[34:35], s[12:13], v0, s2, v[42:43]
	v_add_u32_e32 v0, s10, v0
	ds_read_b128 v[34:37], v34
	v_ashrrev_i32_e32 v38, 31, v0
	v_mul_lo_u32 v40, s0, v38
	v_mul_lo_u32 v41, s1, v0
	v_mad_u64_u32 v[38:39], s[12:13], s0, v0, 0
	v_add_u32_e32 v0, 0x1e00, v43
	v_add3_u32 v39, v39, v40, v41
	v_ashrrev_i32_e32 v0, 5, v0
	v_lshl_add_u64 v[46:47], v[38:39], 1, v[44:45]
	v_mad_u64_u32 v[38:39], s[12:13], v0, s2, v[42:43]
	ds_read_b128 v[38:41], v38
	v_add_u32_e32 v0, s10, v0
	s_waitcnt lgkmcnt(1)
	global_store_dwordx4 v[46:47], v[34:37], off
	s_mov_b64 s[12:13], -1
	s_nop 0
	v_ashrrev_i32_e32 v34, 31, v0
	v_mul_lo_u32 v36, s0, v34
	v_mul_lo_u32 v37, s1, v0
	v_mad_u64_u32 v[34:35], s[0:1], s0, v0, 0
	v_add3_u32 v35, v35, v36, v37
	v_lshl_add_u64 v[34:35], v[34:35], 1, v[44:45]
	s_waitcnt lgkmcnt(0)
	global_store_dwordx4 v[34:35], v[38:41], off
	s_barrier
	s_cbranch_vccz .LBB0_441
